# GEMM phases: one static s_setprio 1 for waves 4-7 (trailing half) at phase entry, reset at phase end
# speedup vs baseline: 1.0058x; 1.0058x over previous
; __device__ __forceinline__ int opaque_tid(int wid_s) { int t = wid_s * 64 + lane_id_hw(); asm volatile("" : "+v"(t)); return t; }
; #define STAGE(bufoff, gbase, voff) do { _Pragma("unroll") for (int _i = 0; _i < 2; ++_i) \
;     __builtin_amdgcn_global_load_lds((const unsigned*)((const char*)(gbase) + (voff)[_i]), (LAS unsigned*)(lds + (bufoff) + ldsw + _i * 8192), 16, 0, 0); } while (0)
; #define WAIT_V(n) asm volatile("s_waitcnt vmcnt(" #n ")" ::: "memory")
; #define BAR __builtin_amdgcn_s_barrier()
; template <int EPI>
; DI void gemm_phase(const int wid_s, const h16* __restrict__ A, const h16* __restrict__ Bt, const int N, const int K, const EpiArgs ea) {
;     ...
;   const int tid = opaque_tid(wid_s), wid = __builtin_amdgcn_readfirstlane(tid >> 6), lane = tid & 63, wr = wid >> 2, wc = wid & 3, fr = lane & 15, fq = lane >> 4;
;   unsigned voffA[2], voffB[2];
; #pragma unroll
;   for (int i = 0; i < 2; ++i) { int R, C; stage_rc(tid * 16 + i * 8192, R, C); const int Rb = (R & ~31) + perm32(R & 31);
;     voffA[i] = (unsigned)(R * K + C) * 2u; voffB[i] = (unsigned)(Rb * K + C) * 2u; }
;   const size_t kstep = (size_t)(BK * 2), hstep = (size_t)HALF * K * 2;
;   const unsigned ldsw = (unsigned)wid * 1024u;
;   const int aoff = lds_byte(wr * 64 + fr, fq * 8), boff = lds_byte(wc * 32 + fr, fq * 8);
;     ...
;   STAGE(SB(0, 0), cB, voffB); STAGE(SB(0, 1), cB + hstep, voffB); STAGE(SA(0, 0), cA, voffA); STAGE(SA(0, 1), cA + hstep, voffA);
;   if (wr == 1) BAR;
;   WAIT_V(2); BAR;
;   STAGE(SB(1, 0), cB + kstep, voffB); STAGE(SA(1, 0), cA + kstep, voffA); STAGE(SB(1, 1), cB + hstep + kstep, voffB);
;   WAIT_V(6); BAR;
.LBB0_112:
	v_lshrrev_b32_e32 v24, 1, v19
	v_and_b32_e32 v24, 24, v24
	v_and_b32_e32 v23, 15, v19
	v_lshlrev_b32_e32 v25, 1, v24
	v_lshlrev_b32_e32 v19, 2, v19
	v_lshl_or_b32 v5, s7, 6, v23
	v_lshl_or_b32 v23, v23, 6, v25
	s_lshl_b32 s7, s7, 13
	v_and_b32_e32 v19, 32, v19
	v_bitop3_b32 v25, v23, s7, v19 bitop3:0xde
	s_lshl_b32 s7, s8, 5
	s_and_b32 s7, s7, 0x60
	s_add_i32 m0, s22, 0x18000
	v_lshl_add_u64 v[12:13], v[12:13], 0, s[36:37]
	s_lshl_b32 s40, s9, 8
	s_lshl_b32 s8, s7, 7
	s_waitcnt vmcnt(2)
	s_barrier
	global_load_lds_dwordx4 v[12:13], off
	v_lshl_add_u64 v[10:11], v[10:11], 0, s[36:37]
	s_add_i32 m0, s22, 0x1a000
	s_add_i32 s27, s22, 0x8000
	s_add_i32 s30, s22, 0xa000
	global_load_lds_dwordx4 v[10:11], off
	v_lshl_add_u64 v[6:7], v[6:7], 0, s[36:37]
	s_mov_b32 m0, s27
	s_add_u32 s4, s4, 0xb0080
	global_load_lds_dwordx4 v[6:7], off
	v_lshl_add_u64 v[6:7], v[8:9], 0, s[36:37]
	s_mov_b32 m0, s30
	s_addc_u32 s5, s5, 0
	global_load_lds_dwordx4 v[6:7], off
	s_add_i32 m0, s22, 0x1c000
	v_lshl_add_u64 v[6:7], s[4:5], 0, v[0:1]
	global_load_lds_dwordx4 v[6:7], off
	v_lshl_add_u64 v[6:7], s[4:5], 0, v[138:139]
	s_add_i32 m0, s22, 0x1e000
	v_bitop3_b32 v148, v23, s8, v19 bitop3:0xde
	global_load_lds_dwordx4 v[6:7], off
	s_movk_i32 s8, 0xb00
	v_lshrrev_b32_e32 v7, 1, v18
	v_mul_lo_u32 v6, v21, s8
	s_mov_b32 s9, 0xb000
	s_cmpk_lt_u32 s6, 0x100
	v_or_b32_e32 v150, s7, v24
	v_mad_u64_u32 v[6:7], s[6:7], v7, s9, v[6:7]
	v_or_b32_e32 v6, v6, v20
	v_add_lshl_u32 v6, v6, v22, 1
	v_mov_b32_e32 v7, v1
	s_mov_b64 s[10:11], 0xb0080
	v_lshl_add_u64 v[140:141], v[6:7], 0, s[10:11]
	v_lshrrev_b32_e32 v7, 1, v14
	v_mul_lo_u32 v6, v16, s8
	v_mad_u64_u32 v[6:7], s[6:7], v7, s9, v[6:7]
	s_waitcnt vmcnt(6)
	v_or_b32_e32 v6, v6, v15
	v_add_lshl_u32 v6, v6, v17, 1
	v_mov_b32_e32 v7, v1
	s_cselect_b64 s[4:5], -1, 0
	v_lshl_add_u64 v[142:143], v[6:7], 0, s[10:11]
	v_add_u32_e32 v151, 0, v25
	s_mov_b32 s31, s39
	s_mov_b32 s38, s40
	s_and_b64 vcc, exec, s[4:5]
	s_cbranch_vccnz .Lgprio_0
	s_setprio 1
.Lgprio_0:
	s_barrier
	s_branch .LBB0_115

; #define WAIT_V(n) asm volatile("s_waitcnt vmcnt(" #n ")" ::: "memory")
; #define BAR __builtin_amdgcn_s_barrier()
; template <int EPI>
; DI void gemm_phase(const int wid_s, const h16* __restrict__ A, const h16* __restrict__ Bt, const int N, const int K, const EpiArgs ea) {
;     ...
;   WAIT_V(0);
;   BAR;
.LBB0_128:
	s_waitcnt vmcnt(0)
	s_setprio 0
	v_readlane_b32 s38, v249, 39
	s_movk_i32 s24, 0x90
	s_movk_i32 s26, 0x1fff
	v_readlane_b32 s39, v249, 40
	s_barrier

; __device__ __forceinline__ int opaque_tid(int wid_s) { int t = wid_s * 64 + lane_id_hw(); asm volatile("" : "+v"(t)); return t; }
; #define STAGE(bufoff, gbase, voff) do { _Pragma("unroll") for (int _i = 0; _i < 2; ++_i) \
;     __builtin_amdgcn_global_load_lds((const unsigned*)((const char*)(gbase) + (voff)[_i]), (LAS unsigned*)(lds + (bufoff) + ldsw + _i * 8192), 16, 0, 0); } while (0)
; #define WAIT_V(n) asm volatile("s_waitcnt vmcnt(" #n ")" ::: "memory")
; #define BAR __builtin_amdgcn_s_barrier()
; template <int EPI>
; DI void gemm_phase(const int wid_s, const h16* __restrict__ A, const h16* __restrict__ Bt, const int N, const int K, const EpiArgs ea) {
;     ...
;   const int tid = opaque_tid(wid_s), wid = __builtin_amdgcn_readfirstlane(tid >> 6), lane = tid & 63, wr = wid >> 2, wc = wid & 3, fr = lane & 15, fq = lane >> 4;
;   unsigned voffA[2], voffB[2];
; #pragma unroll
;   for (int i = 0; i < 2; ++i) { int R, C; stage_rc(tid * 16 + i * 8192, R, C); const int Rb = (R & ~31) + perm32(R & 31);
;     voffA[i] = (unsigned)(R * K + C) * 2u; voffB[i] = (unsigned)(Rb * K + C) * 2u; }
;   const size_t kstep = (size_t)(BK * 2), hstep = (size_t)HALF * K * 2;
;   const unsigned ldsw = (unsigned)wid * 1024u;
;   const int aoff = lds_byte(wr * 64 + fr, fq * 8), boff = lds_byte(wc * 32 + fr, fq * 8);
;     ...
;   STAGE(SB(0, 0), cB, voffB); STAGE(SB(0, 1), cB + hstep, voffB); STAGE(SA(0, 0), cA, voffA); STAGE(SA(0, 1), cA + hstep, voffA);
;   if (wr == 1) BAR;
;   WAIT_V(2); BAR;
;   STAGE(SB(1, 0), cB + kstep, voffB); STAGE(SA(1, 0), cA + kstep, voffA); STAGE(SB(1, 1), cB + hstep + kstep, voffB);
;   WAIT_V(6); BAR;
.LBB0_135:
	s_lshl_b32 s7, s7, 5
	v_and_b32_e32 v21, 15, v20
	s_and_b32 s39, s7, 0x60
	s_add_i32 m0, s17, 0x18000
	v_lshl_add_u64 v[6:7], v[6:7], 0, s[36:37]
	v_lshl_or_b32 v5, s8, 6, v21
	s_lshl_b32 s8, s8, 13
	s_lshl_b32 s7, s39, 7
	s_waitcnt vmcnt(2)
	s_barrier
	global_load_lds_dwordx4 v[6:7], off
	v_lshl_add_u64 v[6:7], v[8:9], 0, s[36:37]
	s_add_i32 m0, s17, 0x1a000
	s_add_i32 s40, s17, 0x8000
	s_add_i32 s41, s17, 0xa000
	global_load_lds_dwordx4 v[6:7], off
	v_lshl_add_u64 v[6:7], v[10:11], 0, s[36:37]
	s_mov_b32 m0, s40
	s_add_u32 s4, s4, 0x40080
	global_load_lds_dwordx4 v[6:7], off
	v_lshl_add_u64 v[6:7], v[12:13], 0, s[36:37]
	s_mov_b32 m0, s41
	s_addc_u32 s5, s5, 0
	global_load_lds_dwordx4 v[6:7], off
	s_add_i32 m0, s17, 0x1c000
	v_lshl_add_u64 v[6:7], s[4:5], 0, v[0:1]
	global_load_lds_dwordx4 v[6:7], off
	v_lshl_add_u64 v[6:7], s[4:5], 0, v[2:3]
	s_add_i32 m0, s17, 0x1e000
	v_bfe_u32 v22, v20, 4, 2
	global_load_lds_dwordx4 v[6:7], off
	v_lshlrev_b32_e32 v6, 14, v14
	v_lshlrev_b32_e32 v23, 4, v22
	v_lshlrev_b32_e32 v20, 2, v20
	v_and_b32_e32 v6, 0xffff8000, v6
	v_lshl_or_b32 v21, v21, 6, v23
	v_and_b32_e32 v20, 32, v20
	v_lshl_add_u32 v6, v15, 11, v6
	v_and_b32_e32 v7, 1, v14
	v_bitop3_b32 v148, v21, s7, v20 bitop3:0xde
	s_cmpk_lt_u32 s6, 0x100
	v_lshl_or_b32 v6, v7, 6, v6
	v_readlane_b32 s6, v249, 25
	v_lshl_add_u32 v6, v16, 1, v6
	v_mov_b32_e32 v7, v1
	v_readlane_b32 s7, v249, 26
	s_waitcnt vmcnt(6)
	v_bitop3_b32 v23, v21, s8, v20 bitop3:0xde
	s_cselect_b64 s[4:5], -1, 0
	v_lshl_add_u64 v[140:141], s[6:7], 0, v[6:7]
	v_lshlrev_b32_e32 v6, 14, v18
	v_and_b32_e32 v6, 0xffff8000, v6
	v_lshl_add_u32 v6, v17, 11, v6
	v_and_b32_e32 v7, 1, v18
	v_lshl_or_b32 v6, v7, 6, v6
	v_lshl_add_u32 v6, v19, 1, v6
	v_mov_b32_e32 v7, v1
	v_lshlrev_b32_e32 v150, 2, v22
	v_lshl_add_u64 v[142:143], s[6:7], 0, v[6:7]
	v_add_u32_e32 v151, 0, v23
	s_and_b64 vcc, exec, s[4:5]
	s_cbranch_vccnz .Lgprio_1
	s_setprio 1

; #define WAIT_V(n) asm volatile("s_waitcnt vmcnt(" #n ")" ::: "memory")
; #define BAR __builtin_amdgcn_s_barrier()
; template <int EPI>
; DI void gemm_phase(const int wid_s, const h16* __restrict__ A, const h16* __restrict__ Bt, const int N, const int K, const EpiArgs ea) {
;     ...
;   WAIT_V(0);
;   BAR;
.LBB0_147:
	s_waitcnt vmcnt(0)
	s_setprio 0
	v_readlane_b32 s38, v249, 39
	v_readlane_b32 s39, v249, 40
	s_barrier

; __device__ __forceinline__ int opaque_tid(int wid_s) { int t = wid_s * 64 + lane_id_hw(); asm volatile("" : "+v"(t)); return t; }
; #define STAGE(bufoff, gbase, voff) do { _Pragma("unroll") for (int _i = 0; _i < 2; ++_i) \
;     __builtin_amdgcn_global_load_lds((const unsigned*)((const char*)(gbase) + (voff)[_i]), (LAS unsigned*)(lds + (bufoff) + ldsw + _i * 8192), 16, 0, 0); } while (0)
; #define WAIT_V(n) asm volatile("s_waitcnt vmcnt(" #n ")" ::: "memory")
; #define BAR __builtin_amdgcn_s_barrier()
; template <int EPI>
; DI void gemm_phase(const int wid_s, const h16* __restrict__ A, const h16* __restrict__ Bt, const int N, const int K, const EpiArgs ea) {
;     ...
;   const int tid = opaque_tid(wid_s), wid = __builtin_amdgcn_readfirstlane(tid >> 6), lane = tid & 63, wr = wid >> 2, wc = wid & 3, fr = lane & 15, fq = lane >> 4;
;   unsigned voffA[2], voffB[2];
; #pragma unroll
;   for (int i = 0; i < 2; ++i) { int R, C; stage_rc(tid * 16 + i * 8192, R, C); const int Rb = (R & ~31) + perm32(R & 31);
;     voffA[i] = (unsigned)(R * K + C) * 2u; voffB[i] = (unsigned)(Rb * K + C) * 2u; }
;   const size_t kstep = (size_t)(BK * 2), hstep = (size_t)HALF * K * 2;
;   const unsigned ldsw = (unsigned)wid * 1024u;
;   const int aoff = lds_byte(wr * 64 + fr, fq * 8), boff = lds_byte(wc * 32 + fr, fq * 8);
;     ...
;   STAGE(SB(0, 0), cB, voffB); STAGE(SB(0, 1), cB + hstep, voffB); STAGE(SA(0, 0), cA, voffA); STAGE(SA(0, 1), cA + hstep, voffA);
;   if (wr == 1) BAR;
;   WAIT_V(2); BAR;
;   STAGE(SB(1, 0), cB + kstep, voffB); STAGE(SA(1, 0), cA + kstep, voffA); STAGE(SB(1, 1), cB + hstep + kstep, voffB);
;   WAIT_V(6); BAR;
.LBB0_165:
	v_lshrrev_b32_e32 v22, 1, v11
	v_and_b32_e32 v22, 24, v22
	v_and_b32_e32 v13, 15, v11
	v_lshlrev_b32_e32 v23, 1, v22
	v_lshlrev_b32_e32 v11, 2, v11
	v_lshl_or_b32 v5, s7, 6, v13
	v_lshl_or_b32 v13, v13, 6, v23
	s_lshl_b32 s7, s7, 13
	v_and_b32_e32 v11, 32, v11
	v_lshl_add_u64 v[14:15], s[4:5], 0, v[0:1]
	v_mov_b32_e32 v139, v1
	v_bitop3_b32 v23, v13, s7, v11 bitop3:0xde
	s_lshl_b32 s7, s8, 5
	v_lshl_add_u64 v[16:17], s[4:5], 0, v[138:139]
	v_mov_b32_e32 v3, v1
	s_and_b32 s7, s7, 0x60
	s_add_i32 m0, s17, 0x18000
	v_lshl_add_u64 v[14:15], v[14:15], 0, s[36:37]
	v_lshl_add_u64 v[18:19], s[22:23], 0, v[2:3]
	v_mov_b32_e32 v135, v1
	s_lshl_b32 s8, s7, 7
	s_waitcnt vmcnt(2)
	s_barrier
	global_load_lds_dwordx4 v[14:15], off
	v_lshl_add_u64 v[14:15], v[16:17], 0, s[36:37]
	s_add_i32 m0, s17, 0x1a000
	s_add_i32 s39, s17, 0x8000
	s_add_i32 s40, s17, 0xa000
	v_lshl_add_u64 v[20:21], s[22:23], 0, v[134:135]
	global_load_lds_dwordx4 v[14:15], off
	v_lshl_add_u64 v[14:15], v[18:19], 0, s[36:37]
	s_mov_b32 m0, s39
	s_add_u32 s4, s4, 0x40080
	global_load_lds_dwordx4 v[14:15], off
	v_lshl_add_u64 v[14:15], v[20:21], 0, s[36:37]
	s_mov_b32 m0, s40
	s_addc_u32 s5, s5, 0
	global_load_lds_dwordx4 v[14:15], off
	s_add_i32 m0, s17, 0x1c000
	v_lshl_add_u64 v[14:15], s[4:5], 0, v[0:1]
	global_load_lds_dwordx4 v[14:15], off
	v_lshl_add_u64 v[14:15], s[4:5], 0, v[138:139]
	s_add_i32 m0, s17, 0x1e000
	v_bitop3_b32 v148, v13, s8, v11 bitop3:0xde
	global_load_lds_dwordx4 v[14:15], off
	v_lshlrev_b32_e32 v11, 14, v9
	v_and_b32_e32 v11, 0xffff8000, v11
	v_lshl_add_u32 v10, v10, 11, v11
	v_and_b32_e32 v9, 1, v9
	v_lshl_or_b32 v9, v9, 6, v10
	v_lshl_add_u32 v140, v12, 1, v9
	v_lshlrev_b32_e32 v9, 14, v6
	v_and_b32_e32 v9, 0xffff8000, v9
	s_waitcnt vmcnt(6)
	v_lshl_add_u32 v7, v7, 11, v9
	v_and_b32_e32 v6, 1, v6
	s_cmpk_lt_u32 s6, 0x100
	v_lshl_or_b32 v6, v6, 6, v7
	s_cselect_b64 s[4:5], -1, 0
	v_or_b32_e32 v150, s7, v22
	v_mov_b32_e32 v141, v1
	v_lshl_add_u32 v142, v8, 1, v6
	v_mov_b32_e32 v143, v1
	v_add_u32_e32 v151, 0, v23
	s_and_b64 vcc, exec, s[4:5]
	s_cbranch_vccnz .Lgprio_2
	s_setprio 1

; __device__ __forceinline__ int opaque_tid(int wid_s) { int t = wid_s * 64 + lane_id_hw(); asm volatile("" : "+v"(t)); return t; }
; #define STAGE(bufoff, gbase, voff) do { _Pragma("unroll") for (int _i = 0; _i < 2; ++_i) \
;     __builtin_amdgcn_global_load_lds((const unsigned*)((const char*)(gbase) + (voff)[_i]), (LAS unsigned*)(lds + (bufoff) + ldsw + _i * 8192), 16, 0, 0); } while (0)
; #define WAIT_V(n) asm volatile("s_waitcnt vmcnt(" #n ")" ::: "memory")
; #define BAR __builtin_amdgcn_s_barrier()
; template <int EPI>
; DI void gemm_phase(const int wid_s, const h16* __restrict__ A, const h16* __restrict__ Bt, const int N, const int K, const EpiArgs ea) {
;     ...
;   const int tid = opaque_tid(wid_s), wid = __builtin_amdgcn_readfirstlane(tid >> 6), lane = tid & 63, wr = wid >> 2, wc = wid & 3, fr = lane & 15, fq = lane >> 4;
;   unsigned voffA[2], voffB[2];
; #pragma unroll
;   for (int i = 0; i < 2; ++i) { int R, C; stage_rc(tid * 16 + i * 8192, R, C); const int Rb = (R & ~31) + perm32(R & 31);
;     voffA[i] = (unsigned)(R * K + C) * 2u; voffB[i] = (unsigned)(Rb * K + C) * 2u; }
;   const size_t kstep = (size_t)(BK * 2), hstep = (size_t)HALF * K * 2;
;   const unsigned ldsw = (unsigned)wid * 1024u;
;   const int aoff = lds_byte(wr * 64 + fr, fq * 8), boff = lds_byte(wc * 32 + fr, fq * 8);
;     ...
;   STAGE(SB(0, 0), cB, voffB); STAGE(SB(0, 1), cB + hstep, voffB); STAGE(SA(0, 0), cA, voffA); STAGE(SA(0, 1), cA + hstep, voffA);
;   if (wr == 1) BAR;
;   WAIT_V(2); BAR;
;   STAGE(SB(1, 0), cB + kstep, voffB); STAGE(SA(1, 0), cA + kstep, voffA); STAGE(SB(1, 1), cB + hstep + kstep, voffB);
;   WAIT_V(6); BAR;
.LBB0_380:
	s_lshl_b32 s8, s8, 5
	s_and_b32 s8, s8, 0x60
	s_add_i32 m0, s13, 0x18000
	v_lshl_add_u64 v[12:13], v[12:13], 0, s[36:37]
	s_lshl_b32 s9, s7, 13
	s_lshl_b32 s10, s8, 7
	s_waitcnt vmcnt(2)
	s_barrier
	global_load_lds_dwordx4 v[12:13], off
	v_lshl_add_u64 v[10:11], v[10:11], 0, s[36:37]
	s_add_i32 m0, s13, 0x1a000
	s_add_i32 s39, s13, 0x8000
	s_add_i32 s40, s13, 0xa000
	global_load_lds_dwordx4 v[10:11], off
	v_lshl_add_u64 v[6:7], v[6:7], 0, s[36:37]
	s_mov_b32 m0, s39
	s_add_u32 s4, s4, 0x40080
	global_load_lds_dwordx4 v[6:7], off
	v_lshl_add_u64 v[6:7], v[8:9], 0, s[36:37]
	s_mov_b32 m0, s40
	s_addc_u32 s5, s5, 0
	global_load_lds_dwordx4 v[6:7], off
	s_add_i32 m0, s13, 0x1c000
	v_lshl_add_u64 v[6:7], s[4:5], 0, v[0:1]
	global_load_lds_dwordx4 v[6:7], off
	v_lshl_add_u64 v[6:7], s[4:5], 0, v[2:3]
	s_add_i32 m0, s13, 0x1e000
	s_cmpk_lt_u32 s6, 0x100
	global_load_lds_dwordx4 v[6:7], off
	v_lshrrev_b32_e32 v7, 1, v14
	v_and_b32_e32 v7, 24, v7
	v_and_b32_e32 v6, 15, v14
	v_lshlrev_b32_e32 v8, 1, v7
	v_lshl_or_b32 v5, s7, 6, v6
	v_lshl_or_b32 v6, v6, 6, v8
	v_lshlrev_b32_e32 v8, 2, v14
	v_and_b32_e32 v8, 32, v8
	v_bitop3_b32 v9, v6, s9, v8 bitop3:0xde
	v_bitop3_b32 v148, v6, s10, v8 bitop3:0xde
	v_lshlrev_b32_e32 v6, 14, v15
	v_and_b32_e32 v6, 0xffff8000, v6
	v_or_b32_e32 v150, s8, v7
	v_lshl_add_u32 v6, v16, 11, v6
	v_and_b32_e32 v7, 1, v15
	v_lshl_or_b32 v6, v7, 6, v6
	v_readlane_b32 s6, v249, 25
	v_lshl_add_u32 v6, v17, 1, v6
	v_mov_b32_e32 v7, v1
	v_readlane_b32 s7, v249, 26
	s_waitcnt vmcnt(6)
	s_cselect_b64 s[4:5], -1, 0
	v_add_u32_e32 v151, 0, v9
	v_lshl_add_u64 v[140:141], s[6:7], 0, v[6:7]
	v_lshlrev_b32_e32 v6, 14, v19
	v_and_b32_e32 v6, 0xffff8000, v6
	v_lshl_add_u32 v6, v18, 11, v6
	v_and_b32_e32 v7, 1, v19
	v_lshl_or_b32 v6, v7, 6, v6
	v_lshl_add_u32 v6, v20, 1, v6
	v_mov_b32_e32 v7, v1
	v_lshl_add_u64 v[142:143], s[6:7], 0, v[6:7]
	s_and_b64 vcc, exec, s[4:5]
	s_cbranch_vccnz .Lgprio_3
	s_setprio 1
